# GQA attention loop rewritten: max-subtraction folded into MFMA C operand, row-sum via ones-MFMA, 3 K/V tiles prefetched in flight
# speedup vs baseline: 1.0060x; 1.0060x over previous
.LBB0_1175:
	s_waitcnt vmcnt(0)
	s_nop 11
	v_mov_b32_e32 v32, v232
	v_div_scale_f32 v33, s[0:1], v32, v32, 1.0
	v_rcp_f32_e32 v34, v33
	v_mov_b32_e32 v91, v131
	v_fma_f32 v35, -v33, v34, 1.0
	v_fmac_f32_e32 v34, v35, v34
	v_div_scale_f32 v35, vcc, 1.0, v32, 1.0
	v_mul_f32_e32 v36, v35, v34
	v_fma_f32 v37, -v33, v36, v35
	v_fmac_f32_e32 v36, v37, v34
	v_fma_f32 v33, -v33, v36, v35
	v_div_fmas_f32 v33, v33, v34, v36
	v_div_fixup_f32 v32, v33, v32, 1.0
	v_pk_mul_f32 v[0:1], v[0:1], v[32:33] op_sel_hi:[1,0]
	v_pk_mul_f32 v[2:3], v[2:3], v[32:33] op_sel_hi:[1,0]
	v_cvt_pk_bf16_f32 v0, v0, v1
	v_cvt_pk_bf16_f32 v1, v2, v3
	v_lshl_add_u64 v[2:3], v[88:89], 0, v[90:91]
	s_barrier
	global_store_dwordx2 v[2:3], v[0:1], off
	v_pk_mul_f32 v[0:1], v[4:5], v[32:33] op_sel_hi:[1,0]
	v_pk_mul_f32 v[4:5], v[6:7], v[32:33] op_sel_hi:[1,0]
	v_cvt_pk_bf16_f32 v0, v0, v1
	v_cvt_pk_bf16_f32 v1, v4, v5
	global_store_dwordx2 v[2:3], v[0:1], off offset:16
	v_pk_mul_f32 v[0:1], v[8:9], v[32:33] op_sel_hi:[1,0]
	v_pk_mul_f32 v[4:5], v[10:11], v[32:33] op_sel_hi:[1,0]
	v_cvt_pk_bf16_f32 v0, v0, v1
	v_cvt_pk_bf16_f32 v1, v4, v5
	global_store_dwordx2 v[2:3], v[0:1], off offset:32
	v_pk_mul_f32 v[0:1], v[12:13], v[32:33] op_sel_hi:[1,0]
	v_pk_mul_f32 v[4:5], v[14:15], v[32:33] op_sel_hi:[1,0]
	v_cvt_pk_bf16_f32 v0, v0, v1
	v_cvt_pk_bf16_f32 v1, v4, v5
	global_store_dwordx2 v[2:3], v[0:1], off offset:48
	v_pk_mul_f32 v[0:1], v[16:17], v[32:33] op_sel_hi:[1,0]
	v_pk_mul_f32 v[4:5], v[18:19], v[32:33] op_sel_hi:[1,0]
	v_cvt_pk_bf16_f32 v0, v0, v1
	v_cvt_pk_bf16_f32 v1, v4, v5
	global_store_dwordx2 v[2:3], v[0:1], off offset:64
	v_pk_mul_f32 v[0:1], v[20:21], v[32:33] op_sel_hi:[1,0]
	v_pk_mul_f32 v[4:5], v[22:23], v[32:33] op_sel_hi:[1,0]
	v_cvt_pk_bf16_f32 v0, v0, v1
	v_cvt_pk_bf16_f32 v1, v4, v5
	global_store_dwordx2 v[2:3], v[0:1], off offset:80
	v_pk_mul_f32 v[0:1], v[24:25], v[32:33] op_sel_hi:[1,0]
	v_pk_mul_f32 v[4:5], v[26:27], v[32:33] op_sel_hi:[1,0]
	v_cvt_pk_bf16_f32 v0, v0, v1
	v_cvt_pk_bf16_f32 v1, v4, v5
	global_store_dwordx2 v[2:3], v[0:1], off offset:96
	v_pk_mul_f32 v[0:1], v[28:29], v[32:33] op_sel_hi:[1,0]
	v_pk_mul_f32 v[4:5], v[30:31], v[32:33] op_sel_hi:[1,0]
	v_cvt_pk_bf16_f32 v0, v0, v1
	v_cvt_pk_bf16_f32 v1, v4, v5
	global_store_dwordx2 v[2:3], v[0:1], off offset:112

.LBB0_1197:
	s_lshl_b32 s5, s0, 8
	s_lshl_b32 s4, s1, 12
	s_and_b32 s5, s5, 0xf00
	s_or_b32 s4, s4, s5
	s_addk_i32 s4, 0x2000
	s_and_b32 s3, s3, 1
	s_mul_hi_i32 s5, s4, 0x1600
	s_mulk_i32 s4, 0x1600
	v_readlane_b32 s6, v254, 62
	v_readlane_b32 s7, v254, 63
	s_add_u32 s6, s6, s4
	s_addc_u32 s7, s7, s5
	s_lshl_b32 s0, s0, 2
	s_lshl_b32 s4, s3, 8
	s_andn2_b32 s0, s0, 63
	s_add_i32 s26, s4, s0
	s_lshl_b64 s[4:5], s[26:27], 1
	s_add_u32 s0, s6, s4
	s_addc_u32 s4, s7, s5
	s_add_u32 s6, s0, 0x1000
	s_addc_u32 s7, s4, 0
	s_mul_i32 s4, s1, 0x110000
	v_readlane_b32 s8, v255, 35
	s_mul_hi_i32 s0, s1, 0x110000
	v_readlane_b32 s9, v255, 36
	s_add_u32 s4, s8, s4
	s_addc_u32 s0, s9, s0
	s_lshl_b32 s5, s3, 6
	s_lshl_b32 s3, s3, 7
	s_add_u32 s8, s4, s3
	s_addc_u32 s9, s0, 0
	s_lshl_b32 s0, s1, 7
	s_or_b32 s0, s0, s5
	s_mul_i32 s4, s0, 0x2200
	v_readlane_b32 s10, v255, 39
	v_mov_b32_e32 v20, v128
	s_mul_hi_i32 s5, s0, 0x2200
	v_readlane_b32 s11, v255, 40
	s_add_u32 s10, s10, s4
	s_addc_u32 s11, s11, s5
	v_readfirstlane_b32 s0, v20
	s_ashr_i32 s0, s0, 1
	v_bfe_u32 v21, v20, 5, 1
	v_mov_b32_e32 v0, s0
	s_movk_i32 s0, 0xffe0
	v_bfi_b32 v2, s0, v0, v20
	v_mov_b64_e32 v[0:1], s[6:7]
	s_movk_i32 s0, 0x1600
	v_ashrrev_i32_e32 v16, 3, v20
	v_mad_i64_i32 v[88:89], s[6:7], v2, s0, v[0:1]
	v_lshlrev_b32_e32 v130, 4, v21
	v_lshlrev_b32_e32 v22, 3, v20
	v_ashrrev_i32_e32 v17, 31, v16
	v_lshl_add_u64 v[0:1], v[88:89], 0, v[130:131]
	v_and_b32_e32 v23, 56, v22
	v_lshlrev_b64 v[18:19], 8, v[16:17]
	global_load_dwordx4 v[76:79], v[0:1], off
	global_load_dwordx4 v[72:75], v[0:1], off offset:32
	global_load_dwordx4 v[68:71], v[0:1], off offset:64
	global_load_dwordx4 v[64:67], v[0:1], off offset:96
	v_lshl_add_u64 v[0:1], s[8:9], 0, v[18:19]
	v_lshlrev_b32_e32 v2, 1, v23
	v_mov_b32_e32 v3, v131
	v_mov_b64_e32 v[4:5], s[10:11]
	s_movk_i32 s8, 0x2200
	v_lshl_add_u64 v[0:1], v[0:1], 0, v[2:3]
	v_mad_i64_i32 v[4:5], s[6:7], v16, s8, v[4:5]
	s_waitcnt vmcnt(63) expcnt(7) lgkmcnt(15)
	s_barrier
	v_lshl_add_u64 v[2:3], v[4:5], 0, v[2:3]
	global_load_dwordx4 v[8:11], v[0:1], off
	global_load_dwordx4 v[12:15], v[2:3], off
	s_movk_i32 s6, 0x48
	v_and_b32_e32 v17, 31, v20
	v_lshlrev_b32_e32 v90, 3, v21
	v_mul_lo_u32 v21, v16, s6
	v_and_b32_e32 v22, 48, v22
	v_lshlrev_b32_e32 v24, 2, v20
	v_lshlrev_b32_e32 v20, 4, v20
	v_mul_u32_u24_e32 v25, 0x48, v17
	v_mul_u32_u24_e32 v93, 0x90, v17
	v_add_u32_e32 v17, v21, v22
	v_mad_i64_i32 v[18:19], s[6:7], s1, v180, v[18:19]
	v_and_b32_e32 v20, 0x70, v20
	v_and_or_b32 v17, v24, 4, v17
	v_readlane_b32 s6, v253, 16
	v_lshlrev_b32_e32 v100, 1, v17
	v_or3_b32 v18, v18, s3, v20
	v_readlane_b32 s7, v253, 17
	v_add_u32_e32 v17, 0, v100
	v_add_lshl_u32 v98, v21, v23, 1
	v_lshl_add_u64 v[94:95], s[6:7], 0, v[18:19]
	v_mov_b64_e32 v[18:19], s[4:5]
	v_add_u32_e32 v22, 0x2000, v17
	v_mad_i64_i32 v[16:17], s[4:5], v16, s8, v[18:19]
	v_add_u32_e32 v21, 0, v98
	v_readlane_b32 s4, v253, 12
	v_or_b32_e32 v16, v16, v20
	v_readlane_b32 s5, v253, 13
	v_mov_b32_e32 v0, v131
	v_mov_b32_e32 v1, v131
	v_mov_b32_e32 v2, v131
	v_mov_b32_e32 v3, v131
	v_mov_b32_e32 v4, v131
	v_mov_b32_e32 v5, v131
	v_mov_b32_e32 v6, v131
	s_waitcnt vmcnt(1)
	ds_write_b128 v21, v[8:11]
	s_waitcnt vmcnt(0)
	ds_write2_b64 v22, v[12:13], v[14:15] offset0:128 offset1:130
	v_mov_b32_e32 v14, v131
	v_mov_b32_e32 v15, v131
	v_mov_b32_e32 v7, v131
	v_add_lshl_u32 v99, v90, v25, 1
	v_lshl_add_u64 v[96:97], s[4:5], 0, v[16:17]
	v_mov_b32_e32 v8, v131
	v_mov_b32_e32 v9, v131
	v_mov_b32_e32 v10, v131
	v_mov_b32_e32 v11, v131
	v_mov_b32_e32 v12, v131
	v_mov_b32_e32 v13, v131
	v_mov_b64_e32 v[30:31], v[14:15]
	s_mov_b32 s0, 0
	v_mov_b32_e32 v91, 0
	v_mov_b32_e32 v92, 0xff800000
	v_mov_b64_e32 v[28:29], v[12:13]
	v_mov_b64_e32 v[26:27], v[10:11]
	v_mov_b64_e32 v[24:25], v[8:9]
	v_mov_b64_e32 v[22:23], v[6:7]
	v_mov_b64_e32 v[20:21], v[4:5]
	v_mov_b64_e32 v[18:19], v[2:3]
	v_mov_b64_e32 v[16:17], v[0:1]
	global_load_dwordx4 v[200:203], v[94:95], off
	global_load_dwordx4 v[204:207], v[96:97], off
	s_mov_b64 s[4:5], 0x4000
	s_nop 0
	v_lshl_add_u64 v[94:95], v[94:95], 0, s[4:5]
	v_lshl_add_u64 v[96:97], v[96:97], 0, s[30:31]
	global_load_dwordx4 v[112:115], v[94:95], off
	global_load_dwordx4 v[116:119], v[96:97], off
	s_mov_b32 s61, 0x53800000
	s_mov_b64 s[62:63], 0
	v_lshl_add_u64 v[94:95], v[94:95], 0, s[4:5]
	v_lshl_add_u64 v[96:97], v[96:97], 0, s[30:31]
	global_load_dwordx4 v[120:123], v[94:95], off
	global_load_dwordx4 v[124:127], v[96:97], off
	s_mov_b64 s[64:65], 0
	s_nop 0
	v_lshl_add_u64 v[94:95], v[94:95], 0, s[4:5]
	v_lshl_add_u64 v[96:97], v[96:97], 0, s[30:31]
	s_waitcnt lgkmcnt(0)
	s_barrier
	v_add_u32_e32 v101, 0, v99
	ds_read_b128 v[182:185], v101
	ds_read_b128 v[186:189], v101 offset:32
	ds_read_b128 v[190:193], v101 offset:64
	ds_read_b128 v[194:197], v101 offset:96
	s_waitcnt lgkmcnt(3)
	v_mfma_f32_32x32x16_bf16 v[48:63], v[182:185], v[76:79], 0
	ds_read_b128 v[182:185], v101 offset:4608
	s_waitcnt lgkmcnt(3)
	v_mfma_f32_32x32x16_bf16 v[48:63], v[186:189], v[72:75], v[48:63]
	ds_read_b128 v[186:189], v101 offset:4640
	s_waitcnt lgkmcnt(3)
	v_mfma_f32_32x32x16_bf16 v[48:63], v[190:193], v[68:71], v[48:63]
	ds_read_b128 v[190:193], v101 offset:4672
	s_waitcnt lgkmcnt(3)
	v_mfma_f32_32x32x16_bf16 v[48:63], v[194:197], v[64:67], v[48:63]
	ds_read_b128 v[194:197], v101 offset:4704
	s_waitcnt lgkmcnt(3)
	v_mfma_f32_32x32x16_bf16 v[32:47], v[182:185], v[76:79], 0
	s_waitcnt lgkmcnt(2)
	v_mfma_f32_32x32x16_bf16 v[32:47], v[186:189], v[72:75], v[32:47]
	s_waitcnt lgkmcnt(1)
	v_mfma_f32_32x32x16_bf16 v[32:47], v[190:193], v[68:71], v[32:47]
	s_waitcnt lgkmcnt(0)
	v_mfma_f32_32x32x16_bf16 v[32:47], v[194:197], v[64:67], v[32:47]
	s_nop 11
	v_max_f32_e32 v101, v32, v48
	v_max3_f32 v101, v101, v49, v33
	v_max3_f32 v101, v101, v50, v34
	v_max3_f32 v101, v101, v51, v35
	v_max3_f32 v101, v101, v52, v36
	v_max3_f32 v101, v101, v53, v37
	v_max3_f32 v101, v101, v54, v38
	v_max3_f32 v101, v101, v55, v39
	v_max3_f32 v101, v101, v56, v40
	v_max3_f32 v101, v101, v57, v41
	v_max3_f32 v101, v101, v58, v42
	v_max3_f32 v101, v101, v59, v43
	v_max3_f32 v101, v101, v60, v44
	v_max3_f32 v101, v101, v61, v45
	v_max3_f32 v101, v101, v62, v46
	v_max3_f32 v101, v101, v63, v47
	v_mov_b32_e32 v102, v101
	s_nop 1
	v_permlane32_swap_b32_e32 v101, v102
	v_max_f32_e32 v101, v101, v102
	v_mul_f32_e32 v216, -1.0, v101
	v_mov_b32_e32 v217, v216
	v_mov_b32_e32 v218, v216
	v_mov_b32_e32 v219, v216
	v_mov_b32_e32 v220, v216
	v_mov_b32_e32 v221, v216
	v_mov_b32_e32 v222, v216
	v_mov_b32_e32 v223, v216
	v_mov_b32_e32 v224, v216
	v_mov_b32_e32 v225, v216
	v_mov_b32_e32 v226, v216
	v_mov_b32_e32 v227, v216
	v_mov_b32_e32 v228, v216
	v_mov_b32_e32 v229, v216
	v_mov_b32_e32 v230, v216
	v_mov_b32_e32 v231, v216
	v_mov_b32_e32 v232, 0
	v_mov_b32_e32 v233, 0
	v_mov_b32_e32 v234, 0
	v_mov_b32_e32 v235, 0
	v_mov_b32_e32 v236, 0
	v_mov_b32_e32 v237, 0
	v_mov_b32_e32 v238, 0
	v_mov_b32_e32 v239, 0
	v_mov_b32_e32 v240, 0
	v_mov_b32_e32 v241, 0
	v_mov_b32_e32 v242, 0
	v_mov_b32_e32 v243, 0
	v_mov_b32_e32 v244, 0
	v_mov_b32_e32 v245, 0
	v_mov_b32_e32 v246, 0
	v_mov_b32_e32 v247, 0
	v_mov_b32_e32 v212, 0x3f803f80
	v_mov_b32_e32 v213, 0x3f803f80
	v_mov_b32_e32 v214, 0x3f803f80
	v_mov_b32_e32 v215, 0x3f803f80
.Lgqa_c0:
	v_lshl_add_u64 v[94:95], v[94:95], 0, s[62:63]
	v_lshl_add_u64 v[96:97], v[96:97], 0, s[64:65]
	s_and_b32 s1, s0, 1
	s_mul_i32 s3, s1, 0x4800
	s_xor_b32 s1, s1, 1
	s_mulk_i32 s1, 0x4800
	v_add_u32_e32 v101, s3, v99
	v_cmp_lt_f32_e32 vcc, s61, v232
	s_cbranch_vccnz .Lgqa_rare0
.Lgqa_rb0:
	ds_read_b128 v[182:185], v101
	ds_read_b128 v[186:189], v101 offset:32
	ds_read_b128 v[190:193], v101 offset:64
	ds_read_b128 v[194:197], v101 offset:96
	s_waitcnt lgkmcnt(3)
	v_mfma_f32_32x32x16_bf16 v[48:63], v[182:185], v[76:79], v[216:231]
	ds_read_b128 v[182:185], v101 offset:4608
	s_waitcnt lgkmcnt(3)
	v_mfma_f32_32x32x16_bf16 v[48:63], v[186:189], v[72:75], v[48:63]
	ds_read_b128 v[186:189], v101 offset:4640
	s_waitcnt lgkmcnt(3)
	v_mfma_f32_32x32x16_bf16 v[48:63], v[190:193], v[68:71], v[48:63]
	ds_read_b128 v[190:193], v101 offset:4672
	s_waitcnt lgkmcnt(3)
	v_mfma_f32_32x32x16_bf16 v[48:63], v[194:197], v[64:67], v[48:63]
	ds_read_b128 v[194:197], v101 offset:4704
	s_waitcnt lgkmcnt(3)
	v_mfma_f32_32x32x16_bf16 v[32:47], v[182:185], v[76:79], v[216:231]
	s_waitcnt lgkmcnt(2)
	v_mfma_f32_32x32x16_bf16 v[32:47], v[186:189], v[72:75], v[32:47]
	s_waitcnt lgkmcnt(1)
	v_mfma_f32_32x32x16_bf16 v[32:47], v[190:193], v[68:71], v[32:47]
	s_waitcnt lgkmcnt(0)
	v_mfma_f32_32x32x16_bf16 v[32:47], v[194:197], v[64:67], v[32:47]
	v_add3_u32 v102, s3, v93, v130
	ds_read_b128 v[182:185], v102 offset:9216
	ds_read_b128 v[80:83], v102 offset:13824
	ds_read_b128 v[186:189], v102 offset:9248
	ds_read_b128 v[84:87], v102 offset:13856
	ds_read_b128 v[104:107], v102 offset:13888
	ds_read_b128 v[108:111], v102 offset:13920
	ds_read_b128 v[190:193], v102 offset:9280
	ds_read_b128 v[194:197], v102 offset:9312
	v_exp_f32_e32 v48, v48
	v_exp_f32_e32 v49, v49
	v_exp_f32_e32 v50, v50
	v_exp_f32_e32 v51, v51
	v_exp_f32_e32 v52, v52
	v_exp_f32_e32 v53, v53
	v_exp_f32_e32 v54, v54
	v_exp_f32_e32 v55, v55
	v_cvt_pk_bf16_f32 v48, v48, v49
	v_cvt_pk_bf16_f32 v49, v50, v51
	v_cvt_pk_bf16_f32 v50, v52, v53
	v_cvt_pk_bf16_f32 v51, v54, v55
	v_exp_f32_e32 v56, v56
	v_exp_f32_e32 v57, v57
	v_exp_f32_e32 v58, v58
	v_exp_f32_e32 v59, v59
	v_exp_f32_e32 v60, v60
	v_exp_f32_e32 v61, v61
	v_exp_f32_e32 v62, v62
	v_exp_f32_e32 v63, v63
	s_waitcnt lgkmcnt(6)
	v_mfma_f32_32x32x16_bf16 v[0:15], v[182:185], v[48:51], v[0:15]
	v_mfma_f32_32x32x16_bf16 v[16:31], v[80:83], v[48:51], v[16:31]
	v_mfma_f32_32x32x16_bf16 v[232:247], v[212:215], v[48:51], v[232:247]
	v_cvt_pk_bf16_f32 v56, v56, v57
	v_cvt_pk_bf16_f32 v57, v58, v59
	v_cvt_pk_bf16_f32 v58, v60, v61
	v_cvt_pk_bf16_f32 v59, v62, v63
	v_exp_f32_e32 v32, v32
	v_exp_f32_e32 v33, v33
	v_exp_f32_e32 v34, v34
	v_exp_f32_e32 v35, v35
	v_exp_f32_e32 v36, v36
	v_exp_f32_e32 v37, v37
	v_exp_f32_e32 v38, v38
	v_exp_f32_e32 v39, v39
	s_waitcnt lgkmcnt(4)
	v_mfma_f32_32x32x16_bf16 v[0:15], v[186:189], v[56:59], v[0:15]
	v_mfma_f32_32x32x16_bf16 v[16:31], v[84:87], v[56:59], v[16:31]
	v_mfma_f32_32x32x16_bf16 v[232:247], v[212:215], v[56:59], v[232:247]
	v_cvt_pk_bf16_f32 v32, v32, v33
	v_cvt_pk_bf16_f32 v33, v34, v35
	v_cvt_pk_bf16_f32 v34, v36, v37
	v_cvt_pk_bf16_f32 v35, v38, v39
	v_exp_f32_e32 v40, v40
	v_exp_f32_e32 v41, v41
	v_exp_f32_e32 v42, v42
	v_exp_f32_e32 v43, v43
	v_exp_f32_e32 v44, v44
	v_exp_f32_e32 v45, v45
	v_exp_f32_e32 v46, v46
	v_exp_f32_e32 v47, v47
	s_waitcnt lgkmcnt(1)
	v_mfma_f32_32x32x16_bf16 v[0:15], v[190:193], v[32:35], v[0:15]
	v_mfma_f32_32x32x16_bf16 v[16:31], v[104:107], v[32:35], v[16:31]
	v_mfma_f32_32x32x16_bf16 v[232:247], v[212:215], v[32:35], v[232:247]
	v_cvt_pk_bf16_f32 v40, v40, v41
	v_cvt_pk_bf16_f32 v41, v42, v43
	v_cvt_pk_bf16_f32 v42, v44, v45
	v_cvt_pk_bf16_f32 v43, v46, v47
	s_add_i32 s0, s0, 1
	s_cmpk_eq_i32 s0, 0x44
	s_waitcnt lgkmcnt(0)
	v_mfma_f32_32x32x16_bf16 v[0:15], v[194:197], v[40:43], v[0:15]
	v_mfma_f32_32x32x16_bf16 v[16:31], v[108:111], v[40:43], v[16:31]
	v_mfma_f32_32x32x16_bf16 v[232:247], v[212:215], v[40:43], v[232:247]
	s_cbranch_scc1 .LBB0_1175
	v_add_u32_e32 v208, s1, v98
	v_add_u32_e32 v209, s1, v100
	s_waitcnt vmcnt(4)
	ds_write_b128 v208, v[200:203]
	v_add_u32_e32 v209, 0x2000, v209
	ds_write2_b64 v209, v[204:205], v[206:207] offset0:128 offset1:130
	s_cmpk_lt_i32 s0, 64
	s_cselect_b32 s62, 0x4000, 0
	s_cselect_b32 s64, 0x80, 0
	s_waitcnt lgkmcnt(0)
	global_load_dwordx4 v[200:203], v[94:95], off
	global_load_dwordx4 v[204:207], v[96:97], off
	s_barrier

.Lgqa_rb1:
	ds_read_b128 v[182:185], v101
	ds_read_b128 v[186:189], v101 offset:32
	ds_read_b128 v[190:193], v101 offset:64
	ds_read_b128 v[194:197], v101 offset:96
	s_waitcnt lgkmcnt(3)
	v_mfma_f32_32x32x16_bf16 v[48:63], v[182:185], v[76:79], v[216:231]
	ds_read_b128 v[182:185], v101 offset:4608
	s_waitcnt lgkmcnt(3)
	v_mfma_f32_32x32x16_bf16 v[48:63], v[186:189], v[72:75], v[48:63]
	ds_read_b128 v[186:189], v101 offset:4640
	s_waitcnt lgkmcnt(3)
	v_mfma_f32_32x32x16_bf16 v[48:63], v[190:193], v[68:71], v[48:63]
	ds_read_b128 v[190:193], v101 offset:4672
	s_waitcnt lgkmcnt(3)
	v_mfma_f32_32x32x16_bf16 v[48:63], v[194:197], v[64:67], v[48:63]
	ds_read_b128 v[194:197], v101 offset:4704
	s_waitcnt lgkmcnt(3)
	v_mfma_f32_32x32x16_bf16 v[32:47], v[182:185], v[76:79], v[216:231]
	s_waitcnt lgkmcnt(2)
	v_mfma_f32_32x32x16_bf16 v[32:47], v[186:189], v[72:75], v[32:47]
	s_waitcnt lgkmcnt(1)
	v_mfma_f32_32x32x16_bf16 v[32:47], v[190:193], v[68:71], v[32:47]
	s_waitcnt lgkmcnt(0)
	v_mfma_f32_32x32x16_bf16 v[32:47], v[194:197], v[64:67], v[32:47]
	v_add3_u32 v102, s3, v93, v130
	ds_read_b128 v[182:185], v102 offset:9216
	ds_read_b128 v[80:83], v102 offset:13824
	ds_read_b128 v[186:189], v102 offset:9248
	ds_read_b128 v[84:87], v102 offset:13856
	ds_read_b128 v[104:107], v102 offset:13888
	ds_read_b128 v[108:111], v102 offset:13920
	ds_read_b128 v[190:193], v102 offset:9280
	ds_read_b128 v[194:197], v102 offset:9312
	v_exp_f32_e32 v48, v48
	v_exp_f32_e32 v49, v49
	v_exp_f32_e32 v50, v50
	v_exp_f32_e32 v51, v51
	v_exp_f32_e32 v52, v52
	v_exp_f32_e32 v53, v53
	v_exp_f32_e32 v54, v54
	v_exp_f32_e32 v55, v55
	v_cvt_pk_bf16_f32 v48, v48, v49
	v_cvt_pk_bf16_f32 v49, v50, v51
	v_cvt_pk_bf16_f32 v50, v52, v53
	v_cvt_pk_bf16_f32 v51, v54, v55
	v_exp_f32_e32 v56, v56
	v_exp_f32_e32 v57, v57
	v_exp_f32_e32 v58, v58
	v_exp_f32_e32 v59, v59
	v_exp_f32_e32 v60, v60
	v_exp_f32_e32 v61, v61
	v_exp_f32_e32 v62, v62
	v_exp_f32_e32 v63, v63
	s_waitcnt lgkmcnt(6)
	v_mfma_f32_32x32x16_bf16 v[0:15], v[182:185], v[48:51], v[0:15]
	v_mfma_f32_32x32x16_bf16 v[16:31], v[80:83], v[48:51], v[16:31]
	v_mfma_f32_32x32x16_bf16 v[232:247], v[212:215], v[48:51], v[232:247]
	v_cvt_pk_bf16_f32 v56, v56, v57
	v_cvt_pk_bf16_f32 v57, v58, v59
	v_cvt_pk_bf16_f32 v58, v60, v61
	v_cvt_pk_bf16_f32 v59, v62, v63
	v_exp_f32_e32 v32, v32
	v_exp_f32_e32 v33, v33
	v_exp_f32_e32 v34, v34
	v_exp_f32_e32 v35, v35
	v_exp_f32_e32 v36, v36
	v_exp_f32_e32 v37, v37
	v_exp_f32_e32 v38, v38
	v_exp_f32_e32 v39, v39
	s_waitcnt lgkmcnt(4)
	v_mfma_f32_32x32x16_bf16 v[0:15], v[186:189], v[56:59], v[0:15]
	v_mfma_f32_32x32x16_bf16 v[16:31], v[84:87], v[56:59], v[16:31]
	v_mfma_f32_32x32x16_bf16 v[232:247], v[212:215], v[56:59], v[232:247]
	v_cvt_pk_bf16_f32 v32, v32, v33
	v_cvt_pk_bf16_f32 v33, v34, v35
	v_cvt_pk_bf16_f32 v34, v36, v37
	v_cvt_pk_bf16_f32 v35, v38, v39
	v_exp_f32_e32 v40, v40
	v_exp_f32_e32 v41, v41
	v_exp_f32_e32 v42, v42
	v_exp_f32_e32 v43, v43
	v_exp_f32_e32 v44, v44
	v_exp_f32_e32 v45, v45
	v_exp_f32_e32 v46, v46
	v_exp_f32_e32 v47, v47
	s_waitcnt lgkmcnt(1)
	v_mfma_f32_32x32x16_bf16 v[0:15], v[190:193], v[32:35], v[0:15]
	v_mfma_f32_32x32x16_bf16 v[16:31], v[104:107], v[32:35], v[16:31]
	v_mfma_f32_32x32x16_bf16 v[232:247], v[212:215], v[32:35], v[232:247]
	v_cvt_pk_bf16_f32 v40, v40, v41
	v_cvt_pk_bf16_f32 v41, v42, v43
	v_cvt_pk_bf16_f32 v42, v44, v45
	v_cvt_pk_bf16_f32 v43, v46, v47
	s_add_i32 s0, s0, 1
	s_cmpk_eq_i32 s0, 0x44
	s_waitcnt lgkmcnt(0)
	v_mfma_f32_32x32x16_bf16 v[0:15], v[194:197], v[40:43], v[0:15]
	v_mfma_f32_32x32x16_bf16 v[16:31], v[108:111], v[40:43], v[16:31]
	v_mfma_f32_32x32x16_bf16 v[232:247], v[212:215], v[40:43], v[232:247]
	s_cbranch_scc1 .LBB0_1175
	v_add_u32_e32 v208, s1, v98
	v_add_u32_e32 v209, s1, v100
	s_waitcnt vmcnt(4)
	ds_write_b128 v208, v[112:115]
	v_add_u32_e32 v209, 0x2000, v209
	ds_write2_b64 v209, v[116:117], v[118:119] offset0:128 offset1:130
	s_cmpk_lt_i32 s0, 64
	s_cselect_b32 s62, 0x4000, 0
	s_cselect_b32 s64, 0x80, 0
	s_waitcnt lgkmcnt(0)
	global_load_dwordx4 v[112:115], v[94:95], off
	global_load_dwordx4 v[116:119], v[96:97], off
	s_barrier

.Lgqa_rb2:
	ds_read_b128 v[182:185], v101
	ds_read_b128 v[186:189], v101 offset:32
	ds_read_b128 v[190:193], v101 offset:64
	ds_read_b128 v[194:197], v101 offset:96
	s_waitcnt lgkmcnt(3)
	v_mfma_f32_32x32x16_bf16 v[48:63], v[182:185], v[76:79], v[216:231]
	ds_read_b128 v[182:185], v101 offset:4608
	s_waitcnt lgkmcnt(3)
	v_mfma_f32_32x32x16_bf16 v[48:63], v[186:189], v[72:75], v[48:63]
	ds_read_b128 v[186:189], v101 offset:4640
	s_waitcnt lgkmcnt(3)
	v_mfma_f32_32x32x16_bf16 v[48:63], v[190:193], v[68:71], v[48:63]
	ds_read_b128 v[190:193], v101 offset:4672
	s_waitcnt lgkmcnt(3)
	v_mfma_f32_32x32x16_bf16 v[48:63], v[194:197], v[64:67], v[48:63]
	ds_read_b128 v[194:197], v101 offset:4704
	s_waitcnt lgkmcnt(3)
	v_mfma_f32_32x32x16_bf16 v[32:47], v[182:185], v[76:79], v[216:231]
	s_waitcnt lgkmcnt(2)
	v_mfma_f32_32x32x16_bf16 v[32:47], v[186:189], v[72:75], v[32:47]
	s_waitcnt lgkmcnt(1)
	v_mfma_f32_32x32x16_bf16 v[32:47], v[190:193], v[68:71], v[32:47]
	s_waitcnt lgkmcnt(0)
	v_mfma_f32_32x32x16_bf16 v[32:47], v[194:197], v[64:67], v[32:47]
	v_add3_u32 v102, s3, v93, v130
	ds_read_b128 v[182:185], v102 offset:9216
	ds_read_b128 v[80:83], v102 offset:13824
	ds_read_b128 v[186:189], v102 offset:9248
	ds_read_b128 v[84:87], v102 offset:13856
	ds_read_b128 v[104:107], v102 offset:13888
	ds_read_b128 v[108:111], v102 offset:13920
	ds_read_b128 v[190:193], v102 offset:9280
	ds_read_b128 v[194:197], v102 offset:9312
	v_exp_f32_e32 v48, v48
	v_exp_f32_e32 v49, v49
	v_exp_f32_e32 v50, v50
	v_exp_f32_e32 v51, v51
	v_exp_f32_e32 v52, v52
	v_exp_f32_e32 v53, v53
	v_exp_f32_e32 v54, v54
	v_exp_f32_e32 v55, v55
	v_cvt_pk_bf16_f32 v48, v48, v49
	v_cvt_pk_bf16_f32 v49, v50, v51
	v_cvt_pk_bf16_f32 v50, v52, v53
	v_cvt_pk_bf16_f32 v51, v54, v55
	v_exp_f32_e32 v56, v56
	v_exp_f32_e32 v57, v57
	v_exp_f32_e32 v58, v58
	v_exp_f32_e32 v59, v59
	v_exp_f32_e32 v60, v60
	v_exp_f32_e32 v61, v61
	v_exp_f32_e32 v62, v62
	v_exp_f32_e32 v63, v63
	s_waitcnt lgkmcnt(6)
	v_mfma_f32_32x32x16_bf16 v[0:15], v[182:185], v[48:51], v[0:15]
	v_mfma_f32_32x32x16_bf16 v[16:31], v[80:83], v[48:51], v[16:31]
	v_mfma_f32_32x32x16_bf16 v[232:247], v[212:215], v[48:51], v[232:247]
	v_cvt_pk_bf16_f32 v56, v56, v57
	v_cvt_pk_bf16_f32 v57, v58, v59
	v_cvt_pk_bf16_f32 v58, v60, v61
	v_cvt_pk_bf16_f32 v59, v62, v63
	v_exp_f32_e32 v32, v32
	v_exp_f32_e32 v33, v33
	v_exp_f32_e32 v34, v34
	v_exp_f32_e32 v35, v35
	v_exp_f32_e32 v36, v36
	v_exp_f32_e32 v37, v37
	v_exp_f32_e32 v38, v38
	v_exp_f32_e32 v39, v39
	s_waitcnt lgkmcnt(4)
	v_mfma_f32_32x32x16_bf16 v[0:15], v[186:189], v[56:59], v[0:15]
	v_mfma_f32_32x32x16_bf16 v[16:31], v[84:87], v[56:59], v[16:31]
	v_mfma_f32_32x32x16_bf16 v[232:247], v[212:215], v[56:59], v[232:247]
	v_cvt_pk_bf16_f32 v32, v32, v33
	v_cvt_pk_bf16_f32 v33, v34, v35
	v_cvt_pk_bf16_f32 v34, v36, v37
	v_cvt_pk_bf16_f32 v35, v38, v39
	v_exp_f32_e32 v40, v40
	v_exp_f32_e32 v41, v41
	v_exp_f32_e32 v42, v42
	v_exp_f32_e32 v43, v43
	v_exp_f32_e32 v44, v44
	v_exp_f32_e32 v45, v45
	v_exp_f32_e32 v46, v46
	v_exp_f32_e32 v47, v47
	s_waitcnt lgkmcnt(1)
	v_mfma_f32_32x32x16_bf16 v[0:15], v[190:193], v[32:35], v[0:15]
	v_mfma_f32_32x32x16_bf16 v[16:31], v[104:107], v[32:35], v[16:31]
	v_mfma_f32_32x32x16_bf16 v[232:247], v[212:215], v[32:35], v[232:247]
	v_cvt_pk_bf16_f32 v40, v40, v41
	v_cvt_pk_bf16_f32 v41, v42, v43
	v_cvt_pk_bf16_f32 v42, v44, v45
	v_cvt_pk_bf16_f32 v43, v46, v47
	s_add_i32 s0, s0, 1
	s_cmpk_eq_i32 s0, 0x44
	s_waitcnt lgkmcnt(0)
	v_mfma_f32_32x32x16_bf16 v[0:15], v[194:197], v[40:43], v[0:15]
	v_mfma_f32_32x32x16_bf16 v[16:31], v[108:111], v[40:43], v[16:31]
	v_mfma_f32_32x32x16_bf16 v[232:247], v[212:215], v[40:43], v[232:247]
	s_cbranch_scc1 .LBB0_1175
	v_add_u32_e32 v208, s1, v98
	v_add_u32_e32 v209, s1, v100
	s_waitcnt vmcnt(4)
	ds_write_b128 v208, v[120:123]
	v_add_u32_e32 v209, 0x2000, v209
	ds_write2_b64 v209, v[124:125], v[126:127] offset0:128 offset1:130
	s_cmpk_lt_i32 s0, 64
	s_cselect_b32 s62, 0x4000, 0
	s_cselect_b32 s64, 0x80, 0
	s_waitcnt lgkmcnt(0)
	global_load_dwordx4 v[120:123], v[94:95], off
	global_load_dwordx4 v[124:127], v[96:97], off
	s_barrier
	s_branch .Lgqa_c0
.Lgqa_rare0:
	v_frexp_exp_i32_f32_e32 v208, v232
	v_sub_u32_e32 v209, 0, v208
	v_cvt_f32_i32_e32 v211, v208
	v_ldexp_f32 v210, 1.0, v209
	v_pk_mul_f32 v[0:1], v[0:1], v[210:211] op_sel_hi:[1,0]
	v_pk_mul_f32 v[2:3], v[2:3], v[210:211] op_sel_hi:[1,0]
	v_pk_mul_f32 v[4:5], v[4:5], v[210:211] op_sel_hi:[1,0]
	v_pk_mul_f32 v[6:7], v[6:7], v[210:211] op_sel_hi:[1,0]
	v_pk_mul_f32 v[8:9], v[8:9], v[210:211] op_sel_hi:[1,0]
	v_pk_mul_f32 v[10:11], v[10:11], v[210:211] op_sel_hi:[1,0]
	v_pk_mul_f32 v[12:13], v[12:13], v[210:211] op_sel_hi:[1,0]
	v_pk_mul_f32 v[14:15], v[14:15], v[210:211] op_sel_hi:[1,0]
	v_pk_mul_f32 v[16:17], v[16:17], v[210:211] op_sel_hi:[1,0]
	v_pk_mul_f32 v[18:19], v[18:19], v[210:211] op_sel_hi:[1,0]
	v_pk_mul_f32 v[20:21], v[20:21], v[210:211] op_sel_hi:[1,0]
	v_pk_mul_f32 v[22:23], v[22:23], v[210:211] op_sel_hi:[1,0]
	v_pk_mul_f32 v[24:25], v[24:25], v[210:211] op_sel_hi:[1,0]
	v_pk_mul_f32 v[26:27], v[26:27], v[210:211] op_sel_hi:[1,0]
	v_pk_mul_f32 v[28:29], v[28:29], v[210:211] op_sel_hi:[1,0]
	v_pk_mul_f32 v[30:31], v[30:31], v[210:211] op_sel_hi:[1,0]
	v_pk_mul_f32 v[232:233], v[232:233], v[210:211] op_sel_hi:[1,0]
	v_pk_mul_f32 v[234:235], v[234:235], v[210:211] op_sel_hi:[1,0]
	v_pk_mul_f32 v[236:237], v[236:237], v[210:211] op_sel_hi:[1,0]
	v_pk_mul_f32 v[238:239], v[238:239], v[210:211] op_sel_hi:[1,0]
	v_pk_mul_f32 v[240:241], v[240:241], v[210:211] op_sel_hi:[1,0]
	v_pk_mul_f32 v[242:243], v[242:243], v[210:211] op_sel_hi:[1,0]
	v_pk_mul_f32 v[244:245], v[244:245], v[210:211] op_sel_hi:[1,0]
	v_pk_mul_f32 v[246:247], v[246:247], v[210:211] op_sel_hi:[1,0]
	v_sub_f32_e32 v216, v216, v211
	v_sub_f32_e32 v217, v217, v211
	v_sub_f32_e32 v218, v218, v211
	v_sub_f32_e32 v219, v219, v211
	v_sub_f32_e32 v220, v220, v211
	v_sub_f32_e32 v221, v221, v211
	v_sub_f32_e32 v222, v222, v211
	v_sub_f32_e32 v223, v223, v211
	v_sub_f32_e32 v224, v224, v211
	v_sub_f32_e32 v225, v225, v211
	v_sub_f32_e32 v226, v226, v211
	v_sub_f32_e32 v227, v227, v211
	v_sub_f32_e32 v228, v228, v211
	v_sub_f32_e32 v229, v229, v211
	v_sub_f32_e32 v230, v230, v211
	v_sub_f32_e32 v231, v231, v211
	s_branch .Lgqa_rb0
